# OUT tail: idle workgroups touch their partner's A operand lines (L2 prefetch, 8 discarded dword loads per thread)
# speedup vs baseline: 1.0060x; 1.0060x over previous
; __device__ __forceinline__ void ph_outproj(Frame& F, int l, float gscale, bool dry) {
;     ...
;     const int nfull = (S.nwg / F.G) * F.G, rem = S.nwg - nfull; const bool split = OUT_HALF_TAIL && !dry && rem > 0 && 2 * rem <= F.G;
;     if (split) S.lim = nfull;
;     pg8::gemm_phase<EpiOut, true, true>(F.lds, F.tid, g, S, E, dry);
;     if (split) { pg8::HalfOrder H{S, nfull}; EpiOut E2 = E; E2.half = true; pg8::gemm_phase<EpiOut, true, true, false, true, pg8::HalfOrder>(F.lds, F.tid, g, H, E2, false); }
.Lout_pf:
	s_sub_i32 s14, s73, s11
	s_cmp_ge_i32 s14, s11
	s_cbranch_scc1 .LBB0_532
	s_ashr_i32 s0, s14, 1
	s_add_i32 s0, s69, s0
	s_ashr_i32 s2, s0, 31
	s_lshr_b32 s2, s2, 29
	s_add_i32 s2, s0, s2
	s_ashr_i32 s3, s2, 3
	s_and_b32 s2, s2, -8
	s_sub_i32 s0, s0, s2
	s_lshr_b32 s1, s47, 1
	s_lshr_b32 s2, s0, 31
	s_or_b32 s1, s2, s1
	s_mul_i32 s0, s1, s0
	s_add_i32 s0, s0, s3
	s_ashr_i32 s1, s0, 31
	s_lshr_b32 s1, s1, 27
	s_add_i32 s1, s0, s1
	s_ashr_i32 s2, s1, 5
	s_lshl_b32 s2, s2, 3
	s_sub_i32 s3, s47, s2
	s_min_i32 s3, s3, 8
	s_abs_i32 s4, s3
	v_cvt_f32_u32_e32 v0, s4
	s_sub_i32 s7, 0, s4
	s_andn2_b32 s1, s1, 31
	s_sub_i32 s0, s0, s1
	v_rcp_iflag_f32_e32 v0, v0
	s_abs_i32 s5, s0
	s_xor_b32 s1, s0, s3
	v_mul_f32_e32 v0, 0x4f7ffffe, v0
	v_cvt_u32_f32_e32 v0, v0
	s_ashr_i32 s1, s1, 31
	v_readfirstlane_b32 s8, v0
	s_mul_i32 s7, s7, s8
	s_mul_hi_u32 s7, s8, s7
	s_add_i32 s8, s8, s7
	s_mul_hi_u32 s7, s5, s8
	s_mul_i32 s8, s7, s4
	s_sub_i32 s5, s5, s8
	s_add_i32 s8, s7, 1
	s_sub_i32 s9, s5, s4
	s_cmp_ge_u32 s5, s4
	s_cselect_b32 s7, s8, s7
	s_cselect_b32 s5, s9, s5
	s_add_i32 s8, s7, 1
	s_cmp_ge_u32 s5, s4
	s_cselect_b32 s4, s8, s7
	s_xor_b32 s4, s4, s1
	s_sub_i32 s4, s4, s1
	s_mul_i32 s1, s4, s3
	s_sub_i32 s0, s0, s1
	s_add_i32 s0, s0, s2
	s_and_b32 s14, s14, 1
	s_ashr_i32 s1, s0, 31
	s_lshl_b64 s[12:13], s[0:1], 19
	s_lshl_b32 s7, s14, 18
	v_readlane_b32 s2, v251, 0
	v_readlane_b32 s3, v251, 1
	v_readlane_b32 s4, v252, 47
	s_add_u32 s2, s2, s12
	s_addc_u32 s3, s3, s13
	s_add_u32 s2, s2, s7
	s_addc_u32 s3, s3, 0
	s_and_b32 s5, s4, 1
	s_lshl_b32 s5, s5, 17
	s_lshr_b32 s4, s4, 1
	s_lshl_b32 s4, s4, 7
	s_or_b32 s5, s5, s4
	v_mbcnt_lo_u32_b32 v0, -1, 0
	v_mbcnt_hi_u32_b32 v0, -1, v0
	v_lshl_add_u32 v0, v0, 11, s5
	s_nop 0
	global_load_dword v2, v0, s[2:3]
	global_load_dword v3, v0, s[2:3] offset:64
	global_load_dword v4, v0, s[2:3] offset:512
	global_load_dword v5, v0, s[2:3] offset:576
	global_load_dword v6, v0, s[2:3] offset:1024
	global_load_dword v7, v0, s[2:3] offset:1088
	global_load_dword v8, v0, s[2:3] offset:1536
	global_load_dword v9, v0, s[2:3] offset:1600
	s_waitcnt vmcnt(0)
	s_branch .LBB0_532
